# on top of v25: attention output stores go through a per-wave LDS half-tile transpose so each store instruction writes 64 contiguous bytes per row (half the L2 write requests)
# baseline (speedup 1.0000x reference)
; #define GAS __attribute__((address_space(1)))
; __device__ __forceinline__ unsigned pkbf(float lo, float hi) { const f32x2_t v = {lo, hi}; const bf16x2_t b = __builtin_convertvector(v, bf16x2_t); return __builtin_bit_cast(unsigned, b); }
; __device__ __forceinline__ void attn_mfma(const GAS bf16* proj, GAS bf16* part, GAS float* lse, int TOKG, const GAS float* qgain, const GAS float* kgain, const GAS float* rel_bias,
;                                           unsigned char* lds, int tid, int lane, int wave, int bid, int G) {
;     ...
;         const float inv = __builtin_amdgcn_rcpf(l);
;         GAS bf16* op = part + ((size_t)p * TOKG + orow) * 1024 + h * 64 + 4 * hh;
; #pragma unroll
;         for (int dt = 0; dt < 2; ++dt)
; #pragma unroll
;             for (int g4 = 0; g4 < 4; ++g4) { v2u w; w.x = pkbf(o[dt][4 * g4] * inv, o[dt][4 * g4 + 1] * inv); w.y = pkbf(o[dt][4 * g4 + 2] * inv, o[dt][4 * g4 + 3] * inv);
;                 *(GAS v2u*)(op + 32 * dt + 8 * g4) = w; }
.LBB0_324:
	s_lshl_b32 s10, -1, s40
	s_andn2_b32 s12, s42, s10
	s_ashr_i32 s10, s39, 4
	s_ashr_i32 s11, s10, 31
	s_lshl_b64 s[10:11], s[10:11], 13
	s_mul_hi_i32 s13, s38, s34
	s_mul_i32 s38, s38, s34
	s_add_u32 s10, s10, s38
	v_lshl_add_u32 v212, s43, 8, v195
	s_addc_u32 s11, s11, s13
	v_ashrrev_i32_e32 v213, 31, v212
	s_waitcnt lgkmcnt(0)
	v_add_f32_e32 v183, v183, v184
	s_add_u32 s10, s10, s12
	v_lshlrev_b64 v[212:213], s40, v[212:213]
	v_rcp_f32_e32 v214, v183
	s_addc_u32 s11, s11, 0
	v_lshl_add_u64 v[184:185], s[10:11], 0, v[212:213]
	s_lshl_b32 s60, s36, 7
	v_pk_mul_f32 v[96:97], v[214:215], v[96:97] op_sel_hi:[0,1]
	v_pk_mul_f32 v[98:99], v[214:215], v[98:99] op_sel_hi:[0,1]
	v_pk_mul_f32 v[100:101], v[214:215], v[100:101] op_sel_hi:[0,1]
	v_pk_mul_f32 v[102:103], v[214:215], v[102:103] op_sel_hi:[0,1]
	v_pk_mul_f32 v[104:105], v[214:215], v[104:105] op_sel_hi:[0,1]
	v_pk_mul_f32 v[106:107], v[214:215], v[106:107] op_sel_hi:[0,1]
	v_pk_mul_f32 v[108:109], v[214:215], v[108:109] op_sel_hi:[0,1]
	v_pk_mul_f32 v[110:111], v[214:215], v[110:111] op_sel_hi:[0,1]
	v_pk_mul_f32 v[80:81], v[214:215], v[80:81] op_sel_hi:[0,1]
	v_pk_mul_f32 v[82:83], v[214:215], v[82:83] op_sel_hi:[0,1]
	v_pk_mul_f32 v[84:85], v[214:215], v[84:85] op_sel_hi:[0,1]
	v_pk_mul_f32 v[86:87], v[214:215], v[86:87] op_sel_hi:[0,1]
	v_pk_mul_f32 v[88:89], v[214:215], v[88:89] op_sel_hi:[0,1]
	v_pk_mul_f32 v[90:91], v[214:215], v[90:91] op_sel_hi:[0,1]
	v_pk_mul_f32 v[92:93], v[214:215], v[92:93] op_sel_hi:[0,1]
	v_pk_mul_f32 v[94:95], v[214:215], v[94:95] op_sel_hi:[0,1]
	v_cvt_pk_bf16_f32 v220, v96, v97
	v_cvt_pk_bf16_f32 v221, v98, v99
	v_cvt_pk_bf16_f32 v222, v100, v101
	v_cvt_pk_bf16_f32 v223, v102, v103
	v_cvt_pk_bf16_f32 v224, v104, v105
	v_cvt_pk_bf16_f32 v225, v106, v107
	v_cvt_pk_bf16_f32 v226, v108, v109
	v_cvt_pk_bf16_f32 v227, v110, v111
	v_cvt_pk_bf16_f32 v228, v80, v81
	v_cvt_pk_bf16_f32 v229, v82, v83
	v_cvt_pk_bf16_f32 v230, v84, v85
	v_cvt_pk_bf16_f32 v231, v86, v87
	v_cvt_pk_bf16_f32 v232, v88, v89
	v_cvt_pk_bf16_f32 v233, v90, v91
	v_cvt_pk_bf16_f32 v234, v92, v93
	v_cvt_pk_bf16_f32 v235, v94, v95
	s_nop 1
	v_permlane32_swap_b32_e32 v220, v222
	v_permlane32_swap_b32_e32 v221, v223
	v_permlane32_swap_b32_e32 v224, v226
	v_permlane32_swap_b32_e32 v225, v227
	v_permlane32_swap_b32_e32 v228, v230
	v_permlane32_swap_b32_e32 v229, v231
	v_permlane32_swap_b32_e32 v232, v234
	v_permlane32_swap_b32_e32 v233, v235
	v_lshrrev_b32_e32 v96, 5, v195
	v_mul_u32_u24_e32 v96, 0xa00, v96
	v_and_b32_e32 v97, 31, v195
	v_mul_u32_u24_e32 v97, 0x50, v97
	v_add_u32_e32 v102, v96, v97
	v_lshl_add_u32 v102, v112, 1, v102
	v_add_u32_e32 v102, 0x20200, v102
	v_lshrrev_b32_e32 v97, 2, v190
	v_mul_u32_u24_e32 v103, 0x50, v97
	v_add_u32_e32 v103, v96, v103
	v_and_b32_e32 v104, 3, v190
	v_lshl_add_u32 v103, v104, 4, v103
	v_add_u32_e32 v103, 0x20200, v103
	v_and_b32_e32 v98, 0xffffffe0, v195
	v_or_b32_e32 v98, v98, v97
	v_lshl_add_u32 v98, s43, 8, v98
	v_ashrrev_i32_e32 v99, 31, v98
	v_lshlrev_b64 v[98:99], s40, v[98:99]
	v_lshl_add_u64 v[98:99], s[10:11], 0, v[98:99]
	v_lshlrev_b64 v[98:99], 11, v[98:99]
	v_lshl_add_u64 v[98:99], s[24:25], 0, v[98:99]
	v_lshl_add_u64 v[98:99], v[98:99], 0, s[60:61]
	v_lshlrev_b32_e32 v100, 4, v104
	v_mov_b32_e32 v101, v113
	v_lshl_add_u64 v[98:99], v[98:99], 0, v[100:101]
	s_lshl_b32 s12, 0x8000, s40
	s_mov_b32 s13, 0
	v_lshl_add_u64 v[100:101], v[98:99], 0, s[12:13]
	ds_write_b128 v102, v[220:223]
	ds_write_b128 v102, v[224:227] offset:32
	ds_read_b128 v[80:83], v103
	ds_read_b128 v[84:87], v103 offset:1280
	ds_write_b128 v102, v[228:231]
	ds_write_b128 v102, v[232:235] offset:32
	ds_read_b128 v[88:91], v103
	ds_read_b128 v[92:95], v103 offset:1280
	s_waitcnt lgkmcnt(0)
	global_store_dwordx4 v[98:99], v[80:83], off
	global_store_dwordx4 v[100:101], v[84:87], off
	global_store_dwordx4 v[98:99], v[88:91], off offset:64
	global_store_dwordx4 v[100:101], v[92:95], off offset:64
	s_and_saveexec_b64 s[10:11], s[8:9]
	s_cbranch_execz .LBB0_289
	v_cmp_gt_f32_e32 vcc, s92, v183
	s_lshl_b32 s60, s36, 2
	s_nop 0
	v_cndmask_b32_e64 v80, 0, 32, vcc
	v_ldexp_f32 v80, v183, v80
	v_log_f32_e32 v80, v80
	v_cndmask_b32_e32 v81, 0, v191, vcc
	v_mul_f32_e32 v82, 0x3f317217, v80
	v_fma_f32 v82, v80, s64, -v82
	v_fmac_f32_e32 v82, 0x3377d1cf, v80
	v_fmac_f32_e32 v82, 0x3f317217, v80
	v_cmp_lt_f32_e64 vcc, |v80|, s65
	s_nop 1
	v_cndmask_b32_e32 v80, v80, v82, vcc
	v_sub_f32_e32 v82, v80, v81
	v_lshlrev_b64 v[80:81], 6, v[184:185]
	v_lshl_add_u64 v[80:81], s[0:1], 0, v[80:81]
	v_lshl_add_u64 v[80:81], v[80:81], 0, s[60:61]
	global_store_dword v[80:81], v82, off
	s_branch .LBB0_289
